# drop per-unit vmcnt(0) at P1 K-loop entry and the no-op vmcnt(8) of the peeled first super-phase (P1, P5)
# speedup vs baseline: 1.0083x; 1.0024x over previous
.LBB0_383:
	s_ashr_i32 s67, s66, 31
	s_lshl_b64 s[26:27], s[66:67], 19
	s_add_u32 s26, s40, s26
	s_addc_u32 s27, s41, s27
	s_and_b64 s[34:35], s[8:9], exec
	s_cselect_b32 s34, s27, s5
	s_cselect_b32 s35, s26, s4
	s_ashr_i32 s29, s28, 31
	s_lshl_b64 s[38:39], s[28:29], 19
	s_add_u32 s62, s10, s38
	s_addc_u32 s63, s11, s39
	s_and_b64 s[38:39], s[8:9], exec
	s_cselect_b32 s29, s63, s83
	s_cselect_b32 s38, s62, s82
	s_add_u32 s39, s82, 0x100
	s_addc_u32 s67, s83, 0
	s_mov_b32 s94, -2
	s_mov_b64 vcc, 0
	v_lshl_add_u64 v[132:133], s[4:5], 0, v[168:169]
	ds_read_b128 v[134:137], v199
	ds_read_b128 v[138:141], v200
	ds_read_b128 v[142:145], v201
	ds_read_b128 v[146:149], v202
	ds_read_b128 v[150:153], v203
	ds_read_b128 v[174:177], v204
	ds_read_b128 v[178:181], v205
	ds_read_b128 v[182:185], v206
	s_add_u32 s24, s4, vcc_lo
	s_addc_u32 s25, s5, vcc_hi
	s_add_u32 s24, s24, 0x100
	s_addc_u32 s25, s25, 0
	s_add_u32 s82, s39, vcc_lo
	s_addc_u32 s83, s67, vcc_hi
	s_cmpk_eq_i32 vcc_lo, 0x700
	s_cselect_b32 s87, s29, s83
	s_cselect_b32 s86, s38, s82
	s_cselect_b32 s83, s34, s25
	s_cselect_b32 s82, s35, s24
	v_lshl_add_u64 v[154:155], v[132:133], 0, vcc
	v_lshl_add_u64 v[250:251], v[154:155], 0, s[48:49]
	s_add_i32 m0, s79, 0x8000
	s_mov_b64 s[24:25], 0x20080
	ds_read_b128 v[218:221], v207
	ds_read_b128 v[222:225], v207 offset:2048
	ds_read_b128 v[226:229], v208
	ds_read_b128 v[230:233], v208 offset:2048
	ds_read_b128 v[234:237], v207 offset:4096
	ds_read_b128 v[238:241], v207 offset:6144
	ds_read_b128 v[242:245], v208 offset:4096
	ds_read_b128 v[246:249], v208 offset:6144
	global_load_lds_dwordx4 v[250:251], off
	v_lshl_add_u64 v[250:251], v[154:155], 0, s[24:25]
	s_add_i32 m0, s79, 0xa000
	s_mov_b64 s[24:25], 0x60080
	global_load_lds_dwordx4 v[250:251], off
	v_lshl_add_u64 v[250:251], v[154:155], 0, s[50:51]
	s_add_i32 m0, s79, 0xc000
	v_lshl_add_u64 v[154:155], v[154:155], 0, s[24:25]
	global_load_lds_dwordx4 v[250:251], off
	s_add_i32 m0, s79, 0xe000
	s_nop 0
	global_load_lds_dwordx4 v[154:155], off
	s_waitcnt lgkmcnt(0)
	s_barrier
	v_mfma_f32_16x16x32_bf16 v[128:131], v[134:137], v[218:221], 0
	v_mfma_f32_16x16x32_bf16 v[124:127], v[142:145], v[218:221], 0
	v_mfma_f32_16x16x32_bf16 v[112:115], v[134:137], v[222:225], 0
	v_mfma_f32_16x16x32_bf16 v[108:111], v[142:145], v[222:225], 0
	v_mfma_f32_16x16x32_bf16 v[96:99], v[134:137], v[234:237], 0
	v_mfma_f32_16x16x32_bf16 v[92:95], v[142:145], v[234:237], 0
	v_mfma_f32_16x16x32_bf16 v[80:83], v[134:137], v[238:241], 0
	v_mfma_f32_16x16x32_bf16 v[76:79], v[142:145], v[238:241], 0
	v_mfma_f32_16x16x32_bf16 v[128:131], v[138:141], v[226:229], v[128:131]
	v_mfma_f32_16x16x32_bf16 v[124:127], v[146:149], v[226:229], v[124:127]
	v_mfma_f32_16x16x32_bf16 v[112:115], v[138:141], v[230:233], v[112:115]
	v_mfma_f32_16x16x32_bf16 v[108:111], v[146:149], v[230:233], v[108:111]
	v_mfma_f32_16x16x32_bf16 v[96:99], v[138:141], v[242:245], v[96:99]
	v_mfma_f32_16x16x32_bf16 v[92:95], v[146:149], v[242:245], v[92:95]
	v_mfma_f32_16x16x32_bf16 v[80:83], v[138:141], v[246:249], v[80:83]
	v_mfma_f32_16x16x32_bf16 v[76:79], v[146:149], v[246:249], v[76:79]
	v_mfma_f32_16x16x32_bf16 v[120:123], v[150:153], v[218:221], 0
	v_mfma_f32_16x16x32_bf16 v[116:119], v[178:181], v[218:221], 0
	v_mfma_f32_16x16x32_bf16 v[104:107], v[150:153], v[222:225], 0
	v_mfma_f32_16x16x32_bf16 v[100:103], v[178:181], v[222:225], 0
	v_mfma_f32_16x16x32_bf16 v[88:91], v[150:153], v[234:237], 0
	v_mfma_f32_16x16x32_bf16 v[84:87], v[178:181], v[234:237], 0
	v_mfma_f32_16x16x32_bf16 v[72:75], v[150:153], v[238:241], 0
	v_mfma_f32_16x16x32_bf16 v[68:71], v[178:181], v[238:241], 0
	v_mfma_f32_16x16x32_bf16 v[120:123], v[174:177], v[226:229], v[120:123]
	v_mfma_f32_16x16x32_bf16 v[116:119], v[182:185], v[226:229], v[116:119]
	v_mfma_f32_16x16x32_bf16 v[104:107], v[174:177], v[230:233], v[104:107]
	v_mfma_f32_16x16x32_bf16 v[100:103], v[182:185], v[230:233], v[100:103]
	v_mfma_f32_16x16x32_bf16 v[88:91], v[174:177], v[242:245], v[88:91]
	v_mfma_f32_16x16x32_bf16 v[84:87], v[182:185], v[242:245], v[84:87]
	v_mfma_f32_16x16x32_bf16 v[72:75], v[174:177], v[246:249], v[72:75]
	v_mfma_f32_16x16x32_bf16 v[68:71], v[182:185], v[246:249], v[68:71]
	s_barrier
	s_add_i32 s24, s1, s77
	v_lshl_add_u64 v[154:155], s[86:87], 0, v[158:159]
	s_mov_b32 m0, s24
	ds_read_b128 v[218:221], v207 offset:16384
	ds_read_b128 v[222:225], v207 offset:18432
	ds_read_b128 v[226:229], v208 offset:16384
	ds_read_b128 v[230:233], v208 offset:18432
	ds_read_b128 v[234:237], v207 offset:20480
	ds_read_b128 v[238:241], v207 offset:22528
	ds_read_b128 v[242:245], v208 offset:20480
	ds_read_b128 v[246:249], v208 offset:22528
	global_load_lds_dwordx4 v[154:155], off
	v_lshl_add_u64 v[250:251], v[154:155], 0, s[14:15]
	s_add_i32 m0, s24, 0x2000
	s_add_i32 s24, s12, s77
	global_load_lds_dwordx4 v[250:251], off
	v_lshl_add_u64 v[250:251], v[154:155], 0, s[16:17]
	s_mov_b32 m0, s24
	s_nop 0
	global_load_lds_dwordx4 v[250:251], off
	v_lshl_add_u64 v[250:251], v[154:155], 0, s[18:19]
	s_add_i32 m0, s24, 0x2000
	s_nop 0
	global_load_lds_dwordx4 v[250:251], off
	s_waitcnt vmcnt(4)
	s_waitcnt lgkmcnt(0)
	s_barrier
	v_mfma_f32_16x16x32_bf16 v[64:67], v[134:137], v[218:221], 0
	v_mfma_f32_16x16x32_bf16 v[60:63], v[142:145], v[218:221], 0
	v_mfma_f32_16x16x32_bf16 v[48:51], v[134:137], v[222:225], 0
	v_mfma_f32_16x16x32_bf16 v[44:47], v[142:145], v[222:225], 0
	v_mfma_f32_16x16x32_bf16 v[32:35], v[134:137], v[234:237], 0
	v_mfma_f32_16x16x32_bf16 v[28:31], v[142:145], v[234:237], 0
	v_mfma_f32_16x16x32_bf16 v[16:19], v[134:137], v[238:241], 0
	v_mfma_f32_16x16x32_bf16 v[12:15], v[142:145], v[238:241], 0
	v_mfma_f32_16x16x32_bf16 v[64:67], v[138:141], v[226:229], v[64:67]
	v_mfma_f32_16x16x32_bf16 v[60:63], v[146:149], v[226:229], v[60:63]
	v_mfma_f32_16x16x32_bf16 v[48:51], v[138:141], v[230:233], v[48:51]
	v_mfma_f32_16x16x32_bf16 v[44:47], v[146:149], v[230:233], v[44:47]
	v_mfma_f32_16x16x32_bf16 v[32:35], v[138:141], v[242:245], v[32:35]
	v_mfma_f32_16x16x32_bf16 v[28:31], v[146:149], v[242:245], v[28:31]
	v_mfma_f32_16x16x32_bf16 v[16:19], v[138:141], v[246:249], v[16:19]
	v_mfma_f32_16x16x32_bf16 v[12:15], v[146:149], v[246:249], v[12:15]
	v_mfma_f32_16x16x32_bf16 v[56:59], v[150:153], v[218:221], 0
	v_mfma_f32_16x16x32_bf16 v[52:55], v[178:181], v[218:221], 0
	v_mfma_f32_16x16x32_bf16 v[40:43], v[150:153], v[222:225], 0
	v_mfma_f32_16x16x32_bf16 v[36:39], v[178:181], v[222:225], 0
	v_mfma_f32_16x16x32_bf16 v[24:27], v[150:153], v[234:237], 0
	v_mfma_f32_16x16x32_bf16 v[20:23], v[178:181], v[234:237], 0
	v_mfma_f32_16x16x32_bf16 v[8:11], v[150:153], v[238:241], 0
	v_mfma_f32_16x16x32_bf16 v[4:7], v[178:181], v[238:241], 0
	v_mfma_f32_16x16x32_bf16 v[56:59], v[174:177], v[226:229], v[56:59]
	v_mfma_f32_16x16x32_bf16 v[52:55], v[182:185], v[226:229], v[52:55]
	v_mfma_f32_16x16x32_bf16 v[40:43], v[174:177], v[230:233], v[40:43]
	v_mfma_f32_16x16x32_bf16 v[36:39], v[182:185], v[230:233], v[36:39]
	v_mfma_f32_16x16x32_bf16 v[24:27], v[174:177], v[242:245], v[24:27]
	v_mfma_f32_16x16x32_bf16 v[20:23], v[182:185], v[242:245], v[20:23]
	v_mfma_f32_16x16x32_bf16 v[8:11], v[174:177], v[246:249], v[8:11]
	v_mfma_f32_16x16x32_bf16 v[4:7], v[182:185], v[246:249], v[4:7]
	s_barrier
	ds_read_b128 v[134:137], v213
	ds_read_b128 v[138:141], v214
	ds_read_b128 v[142:145], v209
	ds_read_b128 v[146:149], v210
	ds_read_b128 v[150:153], v215
	ds_read_b128 v[174:177], v216
	ds_read_b128 v[178:181], v211
	ds_read_b128 v[182:185], v212
	s_mov_b32 m0, s79
	v_lshl_add_u64 v[250:251], s[82:83], 0, v[0:1]
	ds_read_b128 v[218:221], v207 offset:32768
	ds_read_b128 v[222:225], v207 offset:34816
	ds_read_b128 v[226:229], v208 offset:32768
	ds_read_b128 v[230:233], v208 offset:34816
	ds_read_b128 v[234:237], v207 offset:36864
	ds_read_b128 v[238:241], v207 offset:38912
	ds_read_b128 v[242:245], v208 offset:36864
	ds_read_b128 v[246:249], v208 offset:38912
	global_load_lds_dwordx4 v[250:251], off
	v_lshl_add_u64 v[252:253], v[250:251], 0, s[20:21]
	s_mov_b32 m0, s81
	s_nop 0
	global_load_lds_dwordx4 v[252:253], off
	v_lshl_add_u64 v[252:253], v[250:251], 0, s[14:15]
	s_mov_b32 m0, s97
	v_lshl_add_u64 v[250:251], v[250:251], 0, s[22:23]
	global_load_lds_dwordx4 v[252:253], off
	s_mov_b32 m0, s64
	s_nop 0
	global_load_lds_dwordx4 v[250:251], off
	s_waitcnt vmcnt(8)
	s_waitcnt lgkmcnt(0)
	s_barrier
	v_mfma_f32_16x16x32_bf16 v[128:131], v[134:137], v[218:221], v[128:131]
	v_mfma_f32_16x16x32_bf16 v[124:127], v[142:145], v[218:221], v[124:127]
	v_mfma_f32_16x16x32_bf16 v[112:115], v[134:137], v[222:225], v[112:115]
	v_mfma_f32_16x16x32_bf16 v[108:111], v[142:145], v[222:225], v[108:111]
	v_mfma_f32_16x16x32_bf16 v[96:99], v[134:137], v[234:237], v[96:99]
	v_mfma_f32_16x16x32_bf16 v[92:95], v[142:145], v[234:237], v[92:95]
	v_mfma_f32_16x16x32_bf16 v[80:83], v[134:137], v[238:241], v[80:83]
	v_mfma_f32_16x16x32_bf16 v[76:79], v[142:145], v[238:241], v[76:79]
	v_mfma_f32_16x16x32_bf16 v[128:131], v[138:141], v[226:229], v[128:131]
	v_mfma_f32_16x16x32_bf16 v[124:127], v[146:149], v[226:229], v[124:127]
	v_mfma_f32_16x16x32_bf16 v[112:115], v[138:141], v[230:233], v[112:115]
	v_mfma_f32_16x16x32_bf16 v[108:111], v[146:149], v[230:233], v[108:111]
	v_mfma_f32_16x16x32_bf16 v[96:99], v[138:141], v[242:245], v[96:99]
	v_mfma_f32_16x16x32_bf16 v[92:95], v[146:149], v[242:245], v[92:95]
	v_mfma_f32_16x16x32_bf16 v[80:83], v[138:141], v[246:249], v[80:83]
	v_mfma_f32_16x16x32_bf16 v[76:79], v[146:149], v[246:249], v[76:79]
	v_mfma_f32_16x16x32_bf16 v[120:123], v[150:153], v[218:221], v[120:123]
	v_mfma_f32_16x16x32_bf16 v[116:119], v[178:181], v[218:221], v[116:119]
	v_mfma_f32_16x16x32_bf16 v[104:107], v[150:153], v[222:225], v[104:107]
	v_mfma_f32_16x16x32_bf16 v[100:103], v[178:181], v[222:225], v[100:103]
	v_mfma_f32_16x16x32_bf16 v[88:91], v[150:153], v[234:237], v[88:91]
	v_mfma_f32_16x16x32_bf16 v[84:87], v[178:181], v[234:237], v[84:87]
	v_mfma_f32_16x16x32_bf16 v[72:75], v[150:153], v[238:241], v[72:75]
	v_mfma_f32_16x16x32_bf16 v[68:71], v[178:181], v[238:241], v[68:71]
	v_mfma_f32_16x16x32_bf16 v[120:123], v[174:177], v[226:229], v[120:123]
	v_mfma_f32_16x16x32_bf16 v[116:119], v[182:185], v[226:229], v[116:119]
	v_mfma_f32_16x16x32_bf16 v[104:107], v[174:177], v[230:233], v[104:107]
	v_mfma_f32_16x16x32_bf16 v[100:103], v[182:185], v[230:233], v[100:103]
	v_mfma_f32_16x16x32_bf16 v[88:91], v[174:177], v[242:245], v[88:91]
	v_mfma_f32_16x16x32_bf16 v[84:87], v[182:185], v[242:245], v[84:87]
	v_mfma_f32_16x16x32_bf16 v[72:75], v[174:177], v[246:249], v[72:75]
	v_mfma_f32_16x16x32_bf16 v[68:71], v[182:185], v[246:249], v[68:71]
	s_barrier
	s_add_i32 s24, s70, s77
	v_lshl_add_u64 v[250:251], v[154:155], 0, s[48:49]
	s_mov_b32 m0, s24
	ds_read_b128 v[218:221], v207 offset:49152
	ds_read_b128 v[222:225], v207 offset:51200
	ds_read_b128 v[226:229], v208 offset:49152
	ds_read_b128 v[230:233], v208 offset:51200
	ds_read_b128 v[234:237], v207 offset:53248
	ds_read_b128 v[238:241], v207 offset:55296
	ds_read_b128 v[242:245], v208 offset:53248
	ds_read_b128 v[246:249], v208 offset:55296
	global_load_lds_dwordx4 v[250:251], off
	v_lshl_add_u64 v[250:251], v[154:155], 0, s[50:51]
	s_add_i32 m0, s24, 0x2000
	s_add_i32 s24, s71, s77
	global_load_lds_dwordx4 v[250:251], off
	v_lshl_add_u64 v[250:251], v[154:155], 0, s[52:53]
	s_mov_b32 m0, s24
	v_lshl_add_u64 v[154:155], v[154:155], 0, s[54:55]
	global_load_lds_dwordx4 v[250:251], off
	s_add_i32 m0, s24, 0x2000
	s_nop 0
	global_load_lds_dwordx4 v[154:155], off
	s_waitcnt vmcnt(4)
	s_waitcnt lgkmcnt(0)
	s_barrier
	v_mfma_f32_16x16x32_bf16 v[64:67], v[134:137], v[218:221], v[64:67]
	v_mfma_f32_16x16x32_bf16 v[60:63], v[142:145], v[218:221], v[60:63]
	v_mfma_f32_16x16x32_bf16 v[48:51], v[134:137], v[222:225], v[48:51]
	v_mfma_f32_16x16x32_bf16 v[44:47], v[142:145], v[222:225], v[44:47]
	v_mfma_f32_16x16x32_bf16 v[32:35], v[134:137], v[234:237], v[32:35]
	v_mfma_f32_16x16x32_bf16 v[28:31], v[142:145], v[234:237], v[28:31]
	v_mfma_f32_16x16x32_bf16 v[16:19], v[134:137], v[238:241], v[16:19]
	v_mfma_f32_16x16x32_bf16 v[12:15], v[142:145], v[238:241], v[12:15]
	v_mfma_f32_16x16x32_bf16 v[64:67], v[138:141], v[226:229], v[64:67]
	v_mfma_f32_16x16x32_bf16 v[60:63], v[146:149], v[226:229], v[60:63]
	v_mfma_f32_16x16x32_bf16 v[48:51], v[138:141], v[230:233], v[48:51]
	v_mfma_f32_16x16x32_bf16 v[44:47], v[146:149], v[230:233], v[44:47]
	v_mfma_f32_16x16x32_bf16 v[32:35], v[138:141], v[242:245], v[32:35]
	v_mfma_f32_16x16x32_bf16 v[28:31], v[146:149], v[242:245], v[28:31]
	v_mfma_f32_16x16x32_bf16 v[16:19], v[138:141], v[246:249], v[16:19]
	v_mfma_f32_16x16x32_bf16 v[12:15], v[146:149], v[246:249], v[12:15]
	v_mfma_f32_16x16x32_bf16 v[56:59], v[150:153], v[218:221], v[56:59]
	v_mfma_f32_16x16x32_bf16 v[52:55], v[178:181], v[218:221], v[52:55]
	v_mfma_f32_16x16x32_bf16 v[40:43], v[150:153], v[222:225], v[40:43]
	v_mfma_f32_16x16x32_bf16 v[36:39], v[178:181], v[222:225], v[36:39]
	v_mfma_f32_16x16x32_bf16 v[24:27], v[150:153], v[234:237], v[24:27]
	v_mfma_f32_16x16x32_bf16 v[20:23], v[178:181], v[234:237], v[20:23]
	v_mfma_f32_16x16x32_bf16 v[8:11], v[150:153], v[238:241], v[8:11]
	v_mfma_f32_16x16x32_bf16 v[4:7], v[178:181], v[238:241], v[4:7]
	v_mfma_f32_16x16x32_bf16 v[56:59], v[174:177], v[226:229], v[56:59]
	v_mfma_f32_16x16x32_bf16 v[52:55], v[182:185], v[226:229], v[52:55]
	v_mfma_f32_16x16x32_bf16 v[40:43], v[174:177], v[230:233], v[40:43]
	v_mfma_f32_16x16x32_bf16 v[36:39], v[182:185], v[230:233], v[36:39]
	v_mfma_f32_16x16x32_bf16 v[24:27], v[174:177], v[242:245], v[24:27]
	v_mfma_f32_16x16x32_bf16 v[20:23], v[182:185], v[242:245], v[20:23]
	v_mfma_f32_16x16x32_bf16 v[8:11], v[174:177], v[246:249], v[8:11]
	v_mfma_f32_16x16x32_bf16 v[4:7], v[182:185], v[246:249], v[4:7]
	s_barrier
	s_add_i32 s94, s94, 2
	s_add_u32 vcc_lo, vcc_lo, 0x100
	s_addc_u32 vcc_hi, vcc_hi, 0
	s_cmp_gt_u32 s94, 13

.LBB0_1134:
	s_ashr_i32 s57, s56, 31
	s_lshl_b64 s[60:61], s[56:57], 19
	s_add_u32 s60, s42, s60
	s_addc_u32 s61, s43, s61
	s_and_b64 s[62:63], s[10:11], exec
	s_cselect_b32 s57, s61, s27
	s_cselect_b32 s79, s60, s26
	s_ashr_i32 s59, s58, 31
	s_lshl_b64 s[62:63], s[58:59], 19
	v_readlane_b32 s70, v254, 7
	v_readlane_b32 s71, v254, 8
	s_add_u32 s62, s70, s62
	s_addc_u32 s63, s71, s63
	s_and_b64 s[70:71], s[10:11], exec
	s_cselect_b32 s59, s63, s69
	s_cselect_b32 s80, s62, s68
	s_add_u32 s81, s68, 0x100
	v_lshl_add_u64 v[138:139], s[26:27], 0, v[132:133]
	s_addc_u32 s82, s69, 0
	s_mov_b32 s83, -2
	s_mov_b64 s[68:69], 0
	ds_read_b128 v[168:171], v145
	ds_read_b128 v[174:177], v146
	ds_read_b128 v[178:181], v147
	ds_read_b128 v[182:185], v148
	ds_read_b128 v[194:197], v149
	ds_read_b128 v[198:201], v150
	ds_read_b128 v[202:205], v151
	ds_read_b128 v[206:209], v152
	s_add_u32 s70, s26, s68
	s_addc_u32 s71, s27, s69
	s_add_u32 s70, s70, 0x100
	s_addc_u32 s71, s71, 0
	s_add_u32 s84, s81, s68
	s_addc_u32 s85, s82, s69
	s_cmpk_eq_i32 s68, 0x700
	s_cselect_b32 s85, s59, s85
	s_cselect_b32 s84, s80, s84
	s_cselect_b32 s71, s57, s71
	s_cselect_b32 s70, s79, s70
	v_lshl_add_u64 v[140:141], v[138:139], 0, s[68:69]
	v_lshl_add_u64 v[242:243], v[140:141], 0, s[22:23]
	s_add_i32 m0, s34, 0x8000
	s_mov_b64 s[86:87], 0x20080
	ds_read_b128 v[210:213], v153
	ds_read_b128 v[214:217], v153 offset:2048
	ds_read_b128 v[218:221], v154
	ds_read_b128 v[222:225], v154 offset:2048
	ds_read_b128 v[226:229], v153 offset:4096
	ds_read_b128 v[230:233], v153 offset:6144
	ds_read_b128 v[234:237], v154 offset:4096
	ds_read_b128 v[238:241], v154 offset:6144
	global_load_lds_dwordx4 v[242:243], off
	v_lshl_add_u64 v[242:243], v[140:141], 0, s[86:87]
	s_add_i32 m0, s34, 0xa000
	s_mov_b64 s[86:87], 0x60080
	global_load_lds_dwordx4 v[242:243], off
	v_lshl_add_u64 v[242:243], v[140:141], 0, s[24:25]
	s_add_i32 m0, s34, 0xc000
	v_lshl_add_u64 v[140:141], v[140:141], 0, s[86:87]
	global_load_lds_dwordx4 v[242:243], off
	s_add_i32 m0, s34, 0xe000
	s_nop 0
	global_load_lds_dwordx4 v[140:141], off
	s_waitcnt lgkmcnt(0)
	s_barrier
	v_mfma_f32_16x16x32_bf16 v[128:131], v[168:171], v[210:213], 0
	v_mfma_f32_16x16x32_bf16 v[124:127], v[178:181], v[210:213], 0
	v_mfma_f32_16x16x32_bf16 v[112:115], v[168:171], v[214:217], 0
	v_mfma_f32_16x16x32_bf16 v[108:111], v[178:181], v[214:217], 0
	v_mfma_f32_16x16x32_bf16 v[96:99], v[168:171], v[226:229], 0
	v_mfma_f32_16x16x32_bf16 v[92:95], v[178:181], v[226:229], 0
	v_mfma_f32_16x16x32_bf16 v[80:83], v[168:171], v[230:233], 0
	v_mfma_f32_16x16x32_bf16 v[76:79], v[178:181], v[230:233], 0
	v_mfma_f32_16x16x32_bf16 v[128:131], v[174:177], v[218:221], v[128:131]
	v_mfma_f32_16x16x32_bf16 v[124:127], v[182:185], v[218:221], v[124:127]
	v_mfma_f32_16x16x32_bf16 v[112:115], v[174:177], v[222:225], v[112:115]
	v_mfma_f32_16x16x32_bf16 v[108:111], v[182:185], v[222:225], v[108:111]
	v_mfma_f32_16x16x32_bf16 v[96:99], v[174:177], v[234:237], v[96:99]
	v_mfma_f32_16x16x32_bf16 v[92:95], v[182:185], v[234:237], v[92:95]
	v_mfma_f32_16x16x32_bf16 v[80:83], v[174:177], v[238:241], v[80:83]
	v_mfma_f32_16x16x32_bf16 v[76:79], v[182:185], v[238:241], v[76:79]
	v_mfma_f32_16x16x32_bf16 v[120:123], v[194:197], v[210:213], 0
	v_mfma_f32_16x16x32_bf16 v[116:119], v[202:205], v[210:213], 0
	v_mfma_f32_16x16x32_bf16 v[104:107], v[194:197], v[214:217], 0
	v_mfma_f32_16x16x32_bf16 v[100:103], v[202:205], v[214:217], 0
	v_mfma_f32_16x16x32_bf16 v[88:91], v[194:197], v[226:229], 0
	v_mfma_f32_16x16x32_bf16 v[84:87], v[202:205], v[226:229], 0
	v_mfma_f32_16x16x32_bf16 v[72:75], v[194:197], v[230:233], 0
	v_mfma_f32_16x16x32_bf16 v[68:71], v[202:205], v[230:233], 0
	v_mfma_f32_16x16x32_bf16 v[120:123], v[198:201], v[218:221], v[120:123]
	v_mfma_f32_16x16x32_bf16 v[116:119], v[206:209], v[218:221], v[116:119]
	v_mfma_f32_16x16x32_bf16 v[104:107], v[198:201], v[222:225], v[104:107]
	v_mfma_f32_16x16x32_bf16 v[100:103], v[206:209], v[222:225], v[100:103]
	v_mfma_f32_16x16x32_bf16 v[88:91], v[198:201], v[234:237], v[88:91]
	v_mfma_f32_16x16x32_bf16 v[84:87], v[206:209], v[234:237], v[84:87]
	v_mfma_f32_16x16x32_bf16 v[72:75], v[198:201], v[238:241], v[72:75]
	v_mfma_f32_16x16x32_bf16 v[68:71], v[206:209], v[238:241], v[68:71]
	s_barrier
	v_lshl_add_u64 v[140:141], s[84:85], 0, v[158:159]
	s_add_i32 s84, s67, s3
	s_mov_b32 m0, s84
	ds_read_b128 v[210:213], v153 offset:16384
	ds_read_b128 v[214:217], v153 offset:18432
	ds_read_b128 v[218:221], v154 offset:16384
	ds_read_b128 v[222:225], v154 offset:18432
	ds_read_b128 v[226:229], v153 offset:20480
	ds_read_b128 v[230:233], v153 offset:22528
	ds_read_b128 v[234:237], v154 offset:20480
	ds_read_b128 v[238:241], v154 offset:22528
	global_load_lds_dwordx4 v[140:141], off
	v_lshl_add_u64 v[242:243], v[140:141], 0, s[0:1]
	s_add_i32 m0, s84, 0x2000
	s_add_i32 s84, s72, s3
	global_load_lds_dwordx4 v[242:243], off
	v_lshl_add_u64 v[242:243], v[140:141], 0, s[12:13]
	s_mov_b32 m0, s84
	s_nop 0
	global_load_lds_dwordx4 v[242:243], off
	v_lshl_add_u64 v[242:243], v[140:141], 0, s[14:15]
	s_add_i32 m0, s84, 0x2000
	s_nop 0
	global_load_lds_dwordx4 v[242:243], off
	s_waitcnt vmcnt(4)
	s_waitcnt lgkmcnt(0)
	s_barrier
	v_mfma_f32_16x16x32_bf16 v[64:67], v[168:171], v[210:213], 0
	v_mfma_f32_16x16x32_bf16 v[60:63], v[178:181], v[210:213], 0
	v_mfma_f32_16x16x32_bf16 v[48:51], v[168:171], v[214:217], 0
	v_mfma_f32_16x16x32_bf16 v[44:47], v[178:181], v[214:217], 0
	v_mfma_f32_16x16x32_bf16 v[32:35], v[168:171], v[226:229], 0
	v_mfma_f32_16x16x32_bf16 v[28:31], v[178:181], v[226:229], 0
	v_mfma_f32_16x16x32_bf16 v[16:19], v[168:171], v[230:233], 0
	v_mfma_f32_16x16x32_bf16 v[12:15], v[178:181], v[230:233], 0
	v_mfma_f32_16x16x32_bf16 v[64:67], v[174:177], v[218:221], v[64:67]
	v_mfma_f32_16x16x32_bf16 v[60:63], v[182:185], v[218:221], v[60:63]
	v_mfma_f32_16x16x32_bf16 v[48:51], v[174:177], v[222:225], v[48:51]
	v_mfma_f32_16x16x32_bf16 v[44:47], v[182:185], v[222:225], v[44:47]
	v_mfma_f32_16x16x32_bf16 v[32:35], v[174:177], v[234:237], v[32:35]
	v_mfma_f32_16x16x32_bf16 v[28:31], v[182:185], v[234:237], v[28:31]
	v_mfma_f32_16x16x32_bf16 v[16:19], v[174:177], v[238:241], v[16:19]
	v_mfma_f32_16x16x32_bf16 v[12:15], v[182:185], v[238:241], v[12:15]
	v_mfma_f32_16x16x32_bf16 v[56:59], v[194:197], v[210:213], 0
	v_mfma_f32_16x16x32_bf16 v[52:55], v[202:205], v[210:213], 0
	v_mfma_f32_16x16x32_bf16 v[40:43], v[194:197], v[214:217], 0
	v_mfma_f32_16x16x32_bf16 v[36:39], v[202:205], v[214:217], 0
	v_mfma_f32_16x16x32_bf16 v[24:27], v[194:197], v[226:229], 0
	v_mfma_f32_16x16x32_bf16 v[20:23], v[202:205], v[226:229], 0
	v_mfma_f32_16x16x32_bf16 v[8:11], v[194:197], v[230:233], 0
	v_mfma_f32_16x16x32_bf16 v[4:7], v[202:205], v[230:233], 0
	v_mfma_f32_16x16x32_bf16 v[56:59], v[198:201], v[218:221], v[56:59]
	v_mfma_f32_16x16x32_bf16 v[52:55], v[206:209], v[218:221], v[52:55]
	v_mfma_f32_16x16x32_bf16 v[40:43], v[198:201], v[222:225], v[40:43]
	v_mfma_f32_16x16x32_bf16 v[36:39], v[206:209], v[222:225], v[36:39]
	v_mfma_f32_16x16x32_bf16 v[24:27], v[198:201], v[234:237], v[24:27]
	v_mfma_f32_16x16x32_bf16 v[20:23], v[206:209], v[234:237], v[20:23]
	v_mfma_f32_16x16x32_bf16 v[8:11], v[198:201], v[238:241], v[8:11]
	v_mfma_f32_16x16x32_bf16 v[4:7], v[206:209], v[238:241], v[4:7]
	s_barrier
	ds_read_b128 v[168:171], v163
	ds_read_b128 v[174:177], v164
	ds_read_b128 v[178:181], v155
	ds_read_b128 v[182:185], v160
	ds_read_b128 v[194:197], v165
	ds_read_b128 v[198:201], v166
	ds_read_b128 v[202:205], v161
	ds_read_b128 v[206:209], v162
	s_mov_b32 m0, s34
	v_lshl_add_u64 v[242:243], s[70:71], 0, v[0:1]
	ds_read_b128 v[210:213], v153 offset:32768
	ds_read_b128 v[214:217], v153 offset:34816
	ds_read_b128 v[218:221], v154 offset:32768
	ds_read_b128 v[222:225], v154 offset:34816
	ds_read_b128 v[226:229], v153 offset:36864
	ds_read_b128 v[230:233], v153 offset:38912
	ds_read_b128 v[234:237], v154 offset:36864
	ds_read_b128 v[238:241], v154 offset:38912
	global_load_lds_dwordx4 v[242:243], off
	v_lshl_add_u64 v[244:245], v[242:243], 0, s[16:17]
	s_mov_b32 m0, s35
	s_nop 0
	global_load_lds_dwordx4 v[244:245], off
	v_lshl_add_u64 v[244:245], v[242:243], 0, s[0:1]
	s_mov_b32 m0, s38
	v_lshl_add_u64 v[242:243], v[242:243], 0, s[18:19]
	global_load_lds_dwordx4 v[244:245], off
	s_mov_b32 m0, s39
	s_nop 0
	global_load_lds_dwordx4 v[242:243], off
	s_waitcnt vmcnt(8)
	s_waitcnt lgkmcnt(0)
	s_barrier
	v_mfma_f32_16x16x32_bf16 v[128:131], v[168:171], v[210:213], v[128:131]
	v_mfma_f32_16x16x32_bf16 v[124:127], v[178:181], v[210:213], v[124:127]
	v_mfma_f32_16x16x32_bf16 v[112:115], v[168:171], v[214:217], v[112:115]
	v_mfma_f32_16x16x32_bf16 v[108:111], v[178:181], v[214:217], v[108:111]
	v_mfma_f32_16x16x32_bf16 v[96:99], v[168:171], v[226:229], v[96:99]
	v_mfma_f32_16x16x32_bf16 v[92:95], v[178:181], v[226:229], v[92:95]
	v_mfma_f32_16x16x32_bf16 v[80:83], v[168:171], v[230:233], v[80:83]
	v_mfma_f32_16x16x32_bf16 v[76:79], v[178:181], v[230:233], v[76:79]
	v_mfma_f32_16x16x32_bf16 v[128:131], v[174:177], v[218:221], v[128:131]
	v_mfma_f32_16x16x32_bf16 v[124:127], v[182:185], v[218:221], v[124:127]
	v_mfma_f32_16x16x32_bf16 v[112:115], v[174:177], v[222:225], v[112:115]
	v_mfma_f32_16x16x32_bf16 v[108:111], v[182:185], v[222:225], v[108:111]
	v_mfma_f32_16x16x32_bf16 v[96:99], v[174:177], v[234:237], v[96:99]
	v_mfma_f32_16x16x32_bf16 v[92:95], v[182:185], v[234:237], v[92:95]
	v_mfma_f32_16x16x32_bf16 v[80:83], v[174:177], v[238:241], v[80:83]
	v_mfma_f32_16x16x32_bf16 v[76:79], v[182:185], v[238:241], v[76:79]
	v_mfma_f32_16x16x32_bf16 v[120:123], v[194:197], v[210:213], v[120:123]
	v_mfma_f32_16x16x32_bf16 v[116:119], v[202:205], v[210:213], v[116:119]
	v_mfma_f32_16x16x32_bf16 v[104:107], v[194:197], v[214:217], v[104:107]
	v_mfma_f32_16x16x32_bf16 v[100:103], v[202:205], v[214:217], v[100:103]
	v_mfma_f32_16x16x32_bf16 v[88:91], v[194:197], v[226:229], v[88:91]
	v_mfma_f32_16x16x32_bf16 v[84:87], v[202:205], v[226:229], v[84:87]
	v_mfma_f32_16x16x32_bf16 v[72:75], v[194:197], v[230:233], v[72:75]
	v_mfma_f32_16x16x32_bf16 v[68:71], v[202:205], v[230:233], v[68:71]
	v_mfma_f32_16x16x32_bf16 v[120:123], v[198:201], v[218:221], v[120:123]
	v_mfma_f32_16x16x32_bf16 v[116:119], v[206:209], v[218:221], v[116:119]
	v_mfma_f32_16x16x32_bf16 v[104:107], v[198:201], v[222:225], v[104:107]
	v_mfma_f32_16x16x32_bf16 v[100:103], v[206:209], v[222:225], v[100:103]
	v_mfma_f32_16x16x32_bf16 v[88:91], v[198:201], v[234:237], v[88:91]
	v_mfma_f32_16x16x32_bf16 v[84:87], v[206:209], v[234:237], v[84:87]
	v_mfma_f32_16x16x32_bf16 v[72:75], v[198:201], v[238:241], v[72:75]
	v_mfma_f32_16x16x32_bf16 v[68:71], v[206:209], v[238:241], v[68:71]
	s_barrier
	s_add_i32 s70, s73, s3
	v_lshl_add_u64 v[242:243], v[140:141], 0, s[22:23]
	s_mov_b32 m0, s70
	ds_read_b128 v[210:213], v153 offset:49152
	ds_read_b128 v[214:217], v153 offset:51200
	ds_read_b128 v[218:221], v154 offset:49152
	ds_read_b128 v[222:225], v154 offset:51200
	ds_read_b128 v[226:229], v153 offset:53248
	ds_read_b128 v[230:233], v153 offset:55296
	ds_read_b128 v[234:237], v154 offset:53248
	ds_read_b128 v[238:241], v154 offset:55296
	global_load_lds_dwordx4 v[242:243], off
	v_lshl_add_u64 v[242:243], v[140:141], 0, s[24:25]
	s_add_i32 m0, s70, 0x2000
	s_add_i32 s70, s77, s3
	global_load_lds_dwordx4 v[242:243], off
	v_lshl_add_u64 v[242:243], v[140:141], 0, s[28:29]
	s_mov_b32 m0, s70
	v_lshl_add_u64 v[140:141], v[140:141], 0, s[36:37]
	global_load_lds_dwordx4 v[242:243], off
	s_add_i32 m0, s70, 0x2000
	s_nop 0
	global_load_lds_dwordx4 v[140:141], off
	s_waitcnt vmcnt(4)
	s_waitcnt lgkmcnt(0)
	s_barrier
	v_mfma_f32_16x16x32_bf16 v[64:67], v[168:171], v[210:213], v[64:67]
	v_mfma_f32_16x16x32_bf16 v[60:63], v[178:181], v[210:213], v[60:63]
	v_mfma_f32_16x16x32_bf16 v[48:51], v[168:171], v[214:217], v[48:51]
	v_mfma_f32_16x16x32_bf16 v[44:47], v[178:181], v[214:217], v[44:47]
	v_mfma_f32_16x16x32_bf16 v[32:35], v[168:171], v[226:229], v[32:35]
	v_mfma_f32_16x16x32_bf16 v[28:31], v[178:181], v[226:229], v[28:31]
	v_mfma_f32_16x16x32_bf16 v[16:19], v[168:171], v[230:233], v[16:19]
	v_mfma_f32_16x16x32_bf16 v[12:15], v[178:181], v[230:233], v[12:15]
	v_mfma_f32_16x16x32_bf16 v[64:67], v[174:177], v[218:221], v[64:67]
	v_mfma_f32_16x16x32_bf16 v[60:63], v[182:185], v[218:221], v[60:63]
	v_mfma_f32_16x16x32_bf16 v[48:51], v[174:177], v[222:225], v[48:51]
	v_mfma_f32_16x16x32_bf16 v[44:47], v[182:185], v[222:225], v[44:47]
	v_mfma_f32_16x16x32_bf16 v[32:35], v[174:177], v[234:237], v[32:35]
	v_mfma_f32_16x16x32_bf16 v[28:31], v[182:185], v[234:237], v[28:31]
	v_mfma_f32_16x16x32_bf16 v[16:19], v[174:177], v[238:241], v[16:19]
	v_mfma_f32_16x16x32_bf16 v[12:15], v[182:185], v[238:241], v[12:15]
	v_mfma_f32_16x16x32_bf16 v[56:59], v[194:197], v[210:213], v[56:59]
	v_mfma_f32_16x16x32_bf16 v[52:55], v[202:205], v[210:213], v[52:55]
	v_mfma_f32_16x16x32_bf16 v[40:43], v[194:197], v[214:217], v[40:43]
	v_mfma_f32_16x16x32_bf16 v[36:39], v[202:205], v[214:217], v[36:39]
	v_mfma_f32_16x16x32_bf16 v[24:27], v[194:197], v[226:229], v[24:27]
	v_mfma_f32_16x16x32_bf16 v[20:23], v[202:205], v[226:229], v[20:23]
	v_mfma_f32_16x16x32_bf16 v[8:11], v[194:197], v[230:233], v[8:11]
	v_mfma_f32_16x16x32_bf16 v[4:7], v[202:205], v[230:233], v[4:7]
	v_mfma_f32_16x16x32_bf16 v[56:59], v[198:201], v[218:221], v[56:59]
	v_mfma_f32_16x16x32_bf16 v[52:55], v[206:209], v[218:221], v[52:55]
	v_mfma_f32_16x16x32_bf16 v[40:43], v[198:201], v[222:225], v[40:43]
	v_mfma_f32_16x16x32_bf16 v[36:39], v[206:209], v[222:225], v[36:39]
	v_mfma_f32_16x16x32_bf16 v[24:27], v[198:201], v[234:237], v[24:27]
	v_mfma_f32_16x16x32_bf16 v[20:23], v[206:209], v[234:237], v[20:23]
	v_mfma_f32_16x16x32_bf16 v[8:11], v[198:201], v[238:241], v[8:11]
	v_mfma_f32_16x16x32_bf16 v[4:7], v[206:209], v[238:241], v[4:7]
	s_barrier
	s_add_i32 s83, s83, 2
	s_add_u32 s68, s68, 0x100
	s_addc_u32 s69, s69, 0
	s_cmp_gt_u32 s83, 13
